# retention part B (P4): the four gate loads of the output stage issued together instead of one per 16-column block behind the previous block's store
# baseline (speedup 1.0000x reference)
; __device__ __forceinline__ unsigned pk2(float lo, float hi) { return f2bf(lo) | (f2bf(hi) << 16); }
; #define MFMA16(a, b, c) __builtin_amdgcn_mfma_f32_16x16x32_bf16(a, b, c, 0, 0, 0)
; __device__ __forceinline__ void ret2_task(const Params& p_, int l, int task, unsigned char* lds) {
;     ...
;       const int e = tid >> 3, d0 = (tid & 7) * 8; u32x4 o;
;       o.x = pk2(f0[0], f0[1]); o.y = pk2(f0[2], f0[3]); o.z = pk2(f1[0], f1[1]); o.w = pk2(f1[2], f1[3]); *(u32x4*)((bf16*)(lds + R_STF) + e * 72 + d0) = o;
;       o.x = pk2(g0[0], g0[1]); o.y = pk2(g0[2], g0[3]); o.z = pk2(g1[0], g1[1]); o.w = pk2(g1[2], g1[3]); *(u32x4*)((bf16*)(lds + R_STB) + e * 72 + d0) = o; }
;     __syncthreads();
;     const bf16* QS = (const bf16*)(lds + R_QS); const bf16* KS = (const bf16*)(lds + R_KS); const bf16* VT = (const bf16*)(lds + R_VT);
;     const bf16* STF = (const bf16*)(lds + R_STF); const bf16* STB = (const bf16*)(lds + R_STB);
;     bf16x8v qf[2];
; #pragma unroll
;     for (int ks = 0; ks < 2; ++ks) qf[ks] = *(const bf16x8v*)(QS + (16 * w + fr) * 72 + 32 * ks + 8 * fq);
;     const int ai = 16 * w + fr;
;     unsigned pp[8][2];
; #pragma unroll
;     for (int jt = 0; jt < 8; ++jt) { f32x4 acc = {0.f, 0.f, 0.f, 0.f};
; #pragma unroll
;         for (int ks = 0; ks < 2; ++ks) { const bf16x8v kf = *(const bf16x8v*)(KS + (16 * jt + fr) * 72 + 32 * ks + 8 * fq); acc = MFMA16(kf, qf[ks], acc); }
;         float sc[4];
; #pragma unroll
;         for (int r = 0; r < 4; ++r) { const int aj = 16 * jt + 4 * fq + r; const float wg = (aj <= ai) ? exp2f(l2f * (float)(ai - aj)) : exp2f(l2b * (float)(aj - ai)); sc[r] = acc[r] * wg; }
;         pp[jt][0] = pk2(sc[0], sc[1]); pp[jt][1] = pk2(sc[2], sc[3]); }
.LBB0_562:
	v_bfe_u32 v2, v4, 16, 1
	v_add3_u32 v2, v4, v2, s14
	v_bfe_u32 v3, v5, 16, 1
	v_lshrrev_b32_e32 v2, 16, v2
	v_add3_u32 v3, v5, v3, s14
	v_and_or_b32 v2, v3, s15, v2
	v_bfe_u32 v3, v6, 16, 1
	v_add3_u32 v3, v6, v3, s14
	v_bfe_u32 v4, v7, 16, 1
	v_lshrrev_b32_e32 v3, 16, v3
	v_add3_u32 v4, v7, v4, s14
	v_and_or_b32 v3, v4, s15, v3
	v_bfe_u32 v4, v8, 16, 1
	v_add3_u32 v4, v8, v4, s14
	v_bfe_u32 v5, v9, 16, 1
	v_lshrrev_b32_e32 v4, 16, v4
	v_add3_u32 v5, v9, v5, s14
	v_and_or_b32 v4, v5, s15, v4
	v_bfe_u32 v5, v10, 16, 1
	v_add3_u32 v5, v10, v5, s14
	v_bfe_u32 v6, v11, 16, 1
	v_lshrrev_b32_e32 v20, 3, v79
	v_and_b32_e32 v21, 56, v72
	v_lshrrev_b32_e32 v5, 16, v5
	v_add3_u32 v6, v11, v6, s14
	s_movk_i32 s39, 0x90
	v_and_or_b32 v5, v6, s15, v5
	v_mul_lo_u32 v6, v20, s39
	v_lshlrev_b32_e32 v7, 1, v21
	v_readlane_b32 s6, v255, 26
	s_add_i32 s24, 0, 0x18000
	v_bfe_u32 v0, v79, 4, 2
	v_add3_u32 v8, s6, v6, v7
	ds_write_b128 v8, v[2:5]
	v_bfe_u32 v2, v16, 16, 1
	v_add3_u32 v2, v16, v2, s14
	v_bfe_u32 v3, v17, 16, 1
	v_lshrrev_b32_e32 v2, 16, v2
	v_add3_u32 v3, v17, v3, s14
	v_and_or_b32 v2, v3, s15, v2
	v_bfe_u32 v3, v18, 16, 1
	v_add3_u32 v3, v18, v3, s14
	v_bfe_u32 v4, v19, 16, 1
	v_lshrrev_b32_e32 v3, 16, v3
	v_add3_u32 v4, v19, v4, s14
	v_and_or_b32 v3, v4, s15, v3
	v_bfe_u32 v4, v12, 16, 1
	v_add3_u32 v4, v12, v4, s14
	v_bfe_u32 v5, v13, 16, 1
	v_lshrrev_b32_e32 v4, 16, v4
	v_add3_u32 v5, v13, v5, s14
	v_and_or_b32 v4, v5, s15, v4
	v_bfe_u32 v5, v14, 16, 1
	v_add3_u32 v5, v14, v5, s14
	v_bfe_u32 v8, v15, 16, 1
	v_lshrrev_b32_e32 v5, 16, v5
	v_add3_u32 v8, v15, v8, s14
	v_and_or_b32 v5, v8, s15, v5
	v_add3_u32 v6, s24, v6, v7
	ds_write_b128 v6, v[2:5]
	v_ashrrev_i32_e32 v2, 2, v79
	v_lshlrev_b32_e32 v72, 4, v0
	v_and_b32_e32 v71, 15, v79
	v_bfi_b32 v70, -16, v2, v79
	v_add_u32_e32 v10, 0, v72
	v_mad_u64_u32 v[2:3], s[12:13], v70, s39, v[10:11]
	v_mad_u32_u24 v38, v71, s39, v10
	s_waitcnt lgkmcnt(0)
	s_barrier
	ds_read_b128 v[6:9], v2
	ds_read_b128 v[2:5], v2 offset:64
	ds_read_b128 v[10:13], v38 offset:18432
	ds_read_b128 v[80:83], v38 offset:34560
	ds_read_b128 v[14:17], v38 offset:18496
	ds_read_b128 v[18:21], v38 offset:20800
	s_waitcnt lgkmcnt(3)
	v_mfma_f32_16x16x32_bf16 v[10:13], v[10:13], v[6:9], 0
	v_lshlrev_b32_e32 v73, 2, v0
	v_cmp_gt_i32_e32 vcc, v73, v70
	v_or_b32_e32 v39, 0x60, v73
	s_waitcnt lgkmcnt(1)
	v_mfma_f32_16x16x32_bf16 v[10:13], v[14:17], v[2:5], v[10:13]
	v_sub_u32_e32 v14, v73, v70
	v_sub_u32_e32 v15, 0, v14
	v_max_i32_e32 v14, v14, v15
	v_cvt_f32_u32_e32 v14, v14
	v_cndmask_b32_e32 v15, v78, v75, vcc
	v_or_b32_e32 v74, 0x70, v73
	v_mfma_f32_16x16x32_bf16 v[80:83], v[80:83], v[6:9], 0
	v_mul_f32_e32 v16, v15, v14
	v_cmp_gt_f32_e32 vcc, s69, v16
	v_lshlrev_b32_e32 v0, 3, v0
	s_add_i32 s10, s10, s66
	v_cndmask_b32_e32 v16, 0, v183, vcc
	v_fmac_f32_e32 v16, v15, v14
	v_exp_f32_e32 v14, v16
	v_cndmask_b32_e32 v15, 0, v184, vcc
	v_cmp_lt_i32_e32 vcc, v73, v70
	s_add_i32 s3, s3, s66
	v_ldexp_f32 v42, v14, v15
	v_or_b32_e32 v14, 1, v73
	v_sub_u32_e32 v15, v14, v70
	v_sub_u32_e32 v14, v70, v14
	v_cndmask_b32_e32 v14, v15, v14, vcc
	v_cvt_f32_i32_e32 v14, v14
	v_cndmask_b32_e32 v15, v75, v78, vcc
	ds_read_b128 v[22:25], v38 offset:23104
	ds_read_b128 v[26:29], v38 offset:25408
	v_mul_f32_e32 v16, v15, v14
	v_cmp_gt_f32_e32 vcc, s69, v16
	ds_read_b128 v[30:33], v38 offset:27712
	ds_read_b128 v[34:37], v38 offset:30016
	v_cndmask_b32_e32 v16, 0, v183, vcc
	v_fmac_f32_e32 v16, v15, v14
	v_exp_f32_e32 v14, v16
	v_cndmask_b32_e32 v15, 0, v184, vcc
	ds_read_b128 v[66:69], v38 offset:32320
	v_ldexp_f32 v44, v14, v15
	v_or_b32_e32 v14, 2, v73
	v_cmp_gt_i32_e32 vcc, v14, v70
	v_sub_u32_e32 v14, v14, v70
	v_sub_u32_e32 v15, 0, v14
	v_max_i32_e32 v14, v14, v15
	v_cvt_f32_u32_e32 v14, v14
	v_cndmask_b32_e32 v15, v78, v75, vcc
	v_mul_f32_e32 v16, v15, v14
	v_cmp_gt_f32_e32 vcc, s69, v16
	s_nop 1
	v_cndmask_b32_e32 v16, 0, v183, vcc
	v_fmac_f32_e32 v16, v15, v14
	v_exp_f32_e32 v14, v16
	v_cndmask_b32_e32 v15, 0, v184, vcc
	v_ldexp_f32 v43, v14, v15
	v_or_b32_e32 v14, 3, v73
	v_cmp_gt_i32_e32 vcc, v14, v70
	v_sub_u32_e32 v14, v14, v70
	v_sub_u32_e32 v15, 0, v14
	v_max_i32_e32 v14, v14, v15
	v_cvt_f32_u32_e32 v14, v14
	v_cndmask_b32_e32 v15, v78, v75, vcc
	v_mul_f32_e32 v16, v15, v14
	v_cmp_gt_f32_e32 vcc, s69, v16
	s_nop 1
	v_cndmask_b32_e32 v16, 0, v183, vcc
	v_fmac_f32_e32 v16, v15, v14
	v_exp_f32_e32 v14, v16
	v_cndmask_b32_e32 v15, 0, v184, vcc
	v_ldexp_f32 v45, v14, v15
	ds_read_b128 v[14:17], v38 offset:20736
	s_waitcnt lgkmcnt(0)
	v_mfma_f32_16x16x32_bf16 v[14:17], v[14:17], v[6:9], 0
	v_mfma_f32_16x16x32_bf16 v[14:17], v[18:21], v[2:5], v[14:17]
	v_or_b32_e32 v18, 16, v73
	v_cmp_gt_i32_e32 vcc, v18, v70
	v_sub_u32_e32 v18, v18, v70
	v_sub_u32_e32 v19, 0, v18
	v_max_i32_e32 v18, v18, v19
	v_cvt_f32_u32_e32 v18, v18
	v_cndmask_b32_e32 v19, v78, v75, vcc
	v_mul_f32_e32 v20, v19, v18
	v_cmp_gt_f32_e32 vcc, s69, v20
	s_nop 1
	v_cndmask_b32_e32 v20, 0, v183, vcc
	v_fmac_f32_e32 v20, v19, v18
	v_exp_f32_e32 v18, v20
	v_cndmask_b32_e32 v19, 0, v184, vcc
	v_ldexp_f32 v46, v18, v19
	v_or_b32_e32 v18, 17, v73
	v_cmp_gt_i32_e32 vcc, v18, v70
	v_sub_u32_e32 v18, v18, v70
	v_sub_u32_e32 v19, 0, v18
	v_max_i32_e32 v18, v18, v19
	v_cvt_f32_u32_e32 v18, v18
	v_cndmask_b32_e32 v19, v78, v75, vcc
	v_mul_f32_e32 v20, v19, v18
	v_cmp_gt_f32_e32 vcc, s69, v20
	s_nop 1
	v_cndmask_b32_e32 v20, 0, v183, vcc
	v_fmac_f32_e32 v20, v19, v18
	v_exp_f32_e32 v18, v20
	v_cndmask_b32_e32 v19, 0, v184, vcc
	v_ldexp_f32 v48, v18, v19
	v_or_b32_e32 v18, 18, v73
	v_cmp_gt_i32_e32 vcc, v18, v70
	v_sub_u32_e32 v18, v18, v70
	v_sub_u32_e32 v19, 0, v18
	v_max_i32_e32 v18, v18, v19
	v_cvt_f32_u32_e32 v18, v18
	v_cndmask_b32_e32 v19, v78, v75, vcc
	v_mul_f32_e32 v20, v19, v18
	v_cmp_gt_f32_e32 vcc, s69, v20
	s_nop 1
	v_cndmask_b32_e32 v20, 0, v183, vcc
	v_fmac_f32_e32 v20, v19, v18
	v_exp_f32_e32 v18, v20
	v_cndmask_b32_e32 v19, 0, v184, vcc
	v_ldexp_f32 v47, v18, v19
	v_or_b32_e32 v18, 19, v73
	v_cmp_gt_i32_e32 vcc, v18, v70
	v_sub_u32_e32 v18, v18, v70
	v_sub_u32_e32 v19, 0, v18
	v_max_i32_e32 v18, v18, v19
	v_cvt_f32_u32_e32 v18, v18
	v_cndmask_b32_e32 v19, v78, v75, vcc
	v_mul_f32_e32 v20, v19, v18
	v_cmp_gt_f32_e32 vcc, s69, v20
	s_nop 1
	v_cndmask_b32_e32 v20, 0, v183, vcc
	v_fmac_f32_e32 v20, v19, v18
	v_exp_f32_e32 v18, v20
	v_cndmask_b32_e32 v19, 0, v184, vcc
	v_ldexp_f32 v49, v18, v19
	ds_read_b128 v[18:21], v38 offset:23040
	s_waitcnt lgkmcnt(0)
; __device__ __forceinline__ unsigned pk2(float lo, float hi) { return f2bf(lo) | (f2bf(hi) << 16); }
; #define MFMA16(a, b, c) __builtin_amdgcn_mfma_f32_16x16x32_bf16(a, b, c, 0, 0, 0)
; __device__ __forceinline__ void ret2_task(const Params& p_, int l, int task, unsigned char* lds) {
;     ...
;     for (int jt = 0; jt < 8; ++jt) { f32x4 acc = {0.f, 0.f, 0.f, 0.f};
; #pragma unroll
;         for (int ks = 0; ks < 2; ++ks) { const bf16x8v kf = *(const bf16x8v*)(KS + (16 * jt + fr) * 72 + 32 * ks + 8 * fq); acc = MFMA16(kf, qf[ks], acc); }
;         float sc[4];
; #pragma unroll
;         for (int r = 0; r < 4; ++r) { const int aj = 16 * jt + 4 * fq + r; const float wg = (aj <= ai) ? exp2f(l2f * (float)(ai - aj)) : exp2f(l2b * (float)(aj - ai)); sc[r] = acc[r] * wg; }
;         pp[jt][0] = pk2(sc[0], sc[1]); pp[jt][1] = pk2(sc[2], sc[3]); }
	v_mfma_f32_16x16x32_bf16 v[18:21], v[18:21], v[6:9], 0
	v_mfma_f32_16x16x32_bf16 v[18:21], v[22:25], v[2:5], v[18:21]
	v_or_b32_e32 v22, 32, v73
	v_cmp_gt_i32_e32 vcc, v22, v70
	v_sub_u32_e32 v22, v22, v70
	v_sub_u32_e32 v23, 0, v22
	v_max_i32_e32 v22, v22, v23
	v_cvt_f32_u32_e32 v22, v22
	v_cndmask_b32_e32 v23, v78, v75, vcc
	v_mul_f32_e32 v24, v23, v22
	v_cmp_gt_f32_e32 vcc, s69, v24
	s_nop 1
	v_cndmask_b32_e32 v24, 0, v183, vcc
	v_fmac_f32_e32 v24, v23, v22
	v_exp_f32_e32 v22, v24
	v_cndmask_b32_e32 v23, 0, v184, vcc
	v_ldexp_f32 v50, v22, v23
	v_or_b32_e32 v22, 33, v73
	v_cmp_gt_i32_e32 vcc, v22, v70
	v_sub_u32_e32 v22, v22, v70
	v_sub_u32_e32 v23, 0, v22
	v_max_i32_e32 v22, v22, v23
	v_cvt_f32_u32_e32 v22, v22
	v_cndmask_b32_e32 v23, v78, v75, vcc
	v_mul_f32_e32 v24, v23, v22
	v_cmp_gt_f32_e32 vcc, s69, v24
	s_nop 1
	v_cndmask_b32_e32 v24, 0, v183, vcc
	v_fmac_f32_e32 v24, v23, v22
	v_exp_f32_e32 v22, v24
	v_cndmask_b32_e32 v23, 0, v184, vcc
	v_ldexp_f32 v52, v22, v23
	v_or_b32_e32 v22, 34, v73
	v_cmp_gt_i32_e32 vcc, v22, v70
	v_sub_u32_e32 v22, v22, v70
	v_sub_u32_e32 v23, 0, v22
	v_max_i32_e32 v22, v22, v23
	v_cvt_f32_u32_e32 v22, v22
	v_cndmask_b32_e32 v23, v78, v75, vcc
	v_mul_f32_e32 v24, v23, v22
	v_cmp_gt_f32_e32 vcc, s69, v24
	s_nop 1
	v_cndmask_b32_e32 v24, 0, v183, vcc
	v_fmac_f32_e32 v24, v23, v22
	v_exp_f32_e32 v22, v24
	v_cndmask_b32_e32 v23, 0, v184, vcc
	v_ldexp_f32 v51, v22, v23
	v_or_b32_e32 v22, 35, v73
	v_cmp_gt_i32_e32 vcc, v22, v70
	v_sub_u32_e32 v22, v22, v70
	v_sub_u32_e32 v23, 0, v22
	v_max_i32_e32 v22, v22, v23
	v_cvt_f32_u32_e32 v22, v22
	v_cndmask_b32_e32 v23, v78, v75, vcc
	v_mul_f32_e32 v24, v23, v22
	v_cmp_gt_f32_e32 vcc, s69, v24
	s_nop 1
	v_cndmask_b32_e32 v24, 0, v183, vcc
	v_fmac_f32_e32 v24, v23, v22
	v_exp_f32_e32 v22, v24
	v_cndmask_b32_e32 v23, 0, v184, vcc
	v_ldexp_f32 v53, v22, v23
	ds_read_b128 v[22:25], v38 offset:25344
	s_waitcnt lgkmcnt(0)
	v_mfma_f32_16x16x32_bf16 v[22:25], v[22:25], v[6:9], 0
	v_mfma_f32_16x16x32_bf16 v[22:25], v[26:29], v[2:5], v[22:25]
	v_or_b32_e32 v26, 48, v73
	v_cmp_gt_i32_e32 vcc, v26, v70
	v_sub_u32_e32 v26, v26, v70
	v_sub_u32_e32 v27, 0, v26
	v_max_i32_e32 v26, v26, v27
	v_cvt_f32_u32_e32 v26, v26
	v_cndmask_b32_e32 v27, v78, v75, vcc
	v_mul_f32_e32 v28, v27, v26
	v_cmp_gt_f32_e32 vcc, s69, v28
	s_nop 1
	v_cndmask_b32_e32 v28, 0, v183, vcc
	v_fmac_f32_e32 v28, v27, v26
	v_exp_f32_e32 v26, v28
	v_cndmask_b32_e32 v27, 0, v184, vcc
	v_ldexp_f32 v54, v26, v27
	v_or_b32_e32 v26, 49, v73
	v_cmp_gt_i32_e32 vcc, v26, v70
	v_sub_u32_e32 v26, v26, v70
	v_sub_u32_e32 v27, 0, v26
	v_max_i32_e32 v26, v26, v27
	v_cvt_f32_u32_e32 v26, v26
	v_cndmask_b32_e32 v27, v78, v75, vcc
	v_mul_f32_e32 v28, v27, v26
	v_cmp_gt_f32_e32 vcc, s69, v28
	s_nop 1
	v_cndmask_b32_e32 v28, 0, v183, vcc
	v_fmac_f32_e32 v28, v27, v26
	v_exp_f32_e32 v26, v28
	v_cndmask_b32_e32 v27, 0, v184, vcc
	v_ldexp_f32 v56, v26, v27
	v_or_b32_e32 v26, 50, v73
	v_cmp_gt_i32_e32 vcc, v26, v70
	v_sub_u32_e32 v26, v26, v70
	v_sub_u32_e32 v27, 0, v26
	v_max_i32_e32 v26, v26, v27
	v_cvt_f32_u32_e32 v26, v26
	v_cndmask_b32_e32 v27, v78, v75, vcc
	v_mul_f32_e32 v28, v27, v26
	v_cmp_gt_f32_e32 vcc, s69, v28
	s_nop 1
	v_cndmask_b32_e32 v28, 0, v183, vcc
	v_fmac_f32_e32 v28, v27, v26
	v_exp_f32_e32 v26, v28
	v_cndmask_b32_e32 v27, 0, v184, vcc
	v_ldexp_f32 v55, v26, v27
	v_or_b32_e32 v26, 51, v73
	v_cmp_gt_i32_e32 vcc, v26, v70
	v_sub_u32_e32 v26, v26, v70
	v_sub_u32_e32 v27, 0, v26
	v_max_i32_e32 v26, v26, v27
	v_cvt_f32_u32_e32 v26, v26
	v_cndmask_b32_e32 v27, v78, v75, vcc
	v_mul_f32_e32 v28, v27, v26
	v_cmp_gt_f32_e32 vcc, s69, v28
	s_nop 1
	v_cndmask_b32_e32 v28, 0, v183, vcc
	v_fmac_f32_e32 v28, v27, v26
	v_exp_f32_e32 v26, v28
	v_cndmask_b32_e32 v27, 0, v184, vcc
	v_ldexp_f32 v57, v26, v27
	ds_read_b128 v[26:29], v38 offset:27648
	s_waitcnt lgkmcnt(0)
	v_mfma_f32_16x16x32_bf16 v[26:29], v[26:29], v[6:9], 0
	v_mfma_f32_16x16x32_bf16 v[26:29], v[30:33], v[2:5], v[26:29]
	v_or_b32_e32 v30, 64, v73
	v_cmp_gt_i32_e32 vcc, v30, v70
	v_sub_u32_e32 v30, v30, v70
	v_sub_u32_e32 v31, 0, v30
	v_max_i32_e32 v30, v30, v31
	v_cvt_f32_u32_e32 v30, v30
	v_cndmask_b32_e32 v31, v78, v75, vcc
	v_mul_f32_e32 v32, v31, v30
	v_cmp_gt_f32_e32 vcc, s69, v32
	s_nop 1
	v_cndmask_b32_e32 v32, 0, v183, vcc
	v_fmac_f32_e32 v32, v31, v30
	v_exp_f32_e32 v30, v32
	v_cndmask_b32_e32 v31, 0, v184, vcc
	v_ldexp_f32 v58, v30, v31
	v_or_b32_e32 v30, 0x41, v73
	v_cmp_gt_i32_e32 vcc, v30, v70
	v_sub_u32_e32 v30, v30, v70
	v_sub_u32_e32 v31, 0, v30
	v_max_i32_e32 v30, v30, v31
	v_cvt_f32_u32_e32 v30, v30
	v_cndmask_b32_e32 v31, v78, v75, vcc
	v_mul_f32_e32 v32, v31, v30
	v_cmp_gt_f32_e32 vcc, s69, v32
	s_nop 1
	v_cndmask_b32_e32 v32, 0, v183, vcc
	v_fmac_f32_e32 v32, v31, v30
	v_exp_f32_e32 v30, v32
	v_cndmask_b32_e32 v31, 0, v184, vcc
	v_ldexp_f32 v60, v30, v31
	v_or_b32_e32 v30, 0x42, v73
	v_cmp_gt_i32_e32 vcc, v30, v70
	v_sub_u32_e32 v30, v30, v70
	v_sub_u32_e32 v31, 0, v30
	v_max_i32_e32 v30, v30, v31
	v_cvt_f32_u32_e32 v30, v30
	v_cndmask_b32_e32 v31, v78, v75, vcc
	v_mul_f32_e32 v32, v31, v30
	v_cmp_gt_f32_e32 vcc, s69, v32
	s_nop 1
	v_cndmask_b32_e32 v32, 0, v183, vcc
	v_fmac_f32_e32 v32, v31, v30
	v_exp_f32_e32 v30, v32
	v_cndmask_b32_e32 v31, 0, v184, vcc
	v_ldexp_f32 v59, v30, v31
	v_or_b32_e32 v30, 0x43, v73
	v_cmp_gt_i32_e32 vcc, v30, v70
	v_sub_u32_e32 v30, v30, v70
	v_sub_u32_e32 v31, 0, v30
	v_max_i32_e32 v30, v30, v31
	v_cvt_f32_u32_e32 v30, v30
	v_cndmask_b32_e32 v31, v78, v75, vcc
	v_mul_f32_e32 v32, v31, v30
	v_cmp_gt_f32_e32 vcc, s69, v32
	s_nop 1
	v_cndmask_b32_e32 v32, 0, v183, vcc
	v_fmac_f32_e32 v32, v31, v30
	v_exp_f32_e32 v30, v32
	v_cndmask_b32_e32 v31, 0, v184, vcc
	v_ldexp_f32 v61, v30, v31
	ds_read_b128 v[30:33], v38 offset:29952
	s_waitcnt lgkmcnt(0)
; __device__ __forceinline__ unsigned pk2(float lo, float hi) { return f2bf(lo) | (f2bf(hi) << 16); }
; #define MFMA16(a, b, c) __builtin_amdgcn_mfma_f32_16x16x32_bf16(a, b, c, 0, 0, 0)
; __device__ __forceinline__ void ret2_task(const Params& p_, int l, int task, unsigned char* lds) {
;     ...
;     for (int jt = 0; jt < 8; ++jt) { f32x4 acc = {0.f, 0.f, 0.f, 0.f};
; #pragma unroll
;         for (int ks = 0; ks < 2; ++ks) { const bf16x8v kf = *(const bf16x8v*)(KS + (16 * jt + fr) * 72 + 32 * ks + 8 * fq); acc = MFMA16(kf, qf[ks], acc); }
;         float sc[4];
; #pragma unroll
;         for (int r = 0; r < 4; ++r) { const int aj = 16 * jt + 4 * fq + r; const float wg = (aj <= ai) ? exp2f(l2f * (float)(ai - aj)) : exp2f(l2b * (float)(aj - ai)); sc[r] = acc[r] * wg; }
;         pp[jt][0] = pk2(sc[0], sc[1]); pp[jt][1] = pk2(sc[2], sc[3]); }
	v_mfma_f32_16x16x32_bf16 v[30:33], v[30:33], v[6:9], 0
	v_mfma_f32_16x16x32_bf16 v[30:33], v[34:37], v[2:5], v[30:33]
	v_or_b32_e32 v34, 0x50, v73
	v_cmp_gt_i32_e32 vcc, v34, v70
	v_sub_u32_e32 v34, v34, v70
	v_sub_u32_e32 v35, 0, v34
	v_max_i32_e32 v34, v34, v35
	v_cvt_f32_u32_e32 v34, v34
	v_cndmask_b32_e32 v35, v78, v75, vcc
	v_mul_f32_e32 v36, v35, v34
	v_cmp_gt_f32_e32 vcc, s69, v36
	s_nop 1
	v_cndmask_b32_e32 v36, 0, v183, vcc
	v_fmac_f32_e32 v36, v35, v34
	v_exp_f32_e32 v34, v36
	v_cndmask_b32_e32 v35, 0, v184, vcc
	v_ldexp_f32 v62, v34, v35
	v_or_b32_e32 v34, 0x51, v73
	v_cmp_gt_i32_e32 vcc, v34, v70
	v_sub_u32_e32 v34, v34, v70
	v_sub_u32_e32 v35, 0, v34
	v_max_i32_e32 v34, v34, v35
	v_cvt_f32_u32_e32 v34, v34
	v_cndmask_b32_e32 v35, v78, v75, vcc
	v_mul_f32_e32 v36, v35, v34
	v_cmp_gt_f32_e32 vcc, s69, v36
	s_nop 1
	v_cndmask_b32_e32 v36, 0, v183, vcc
	v_fmac_f32_e32 v36, v35, v34
	v_exp_f32_e32 v34, v36
	v_cndmask_b32_e32 v35, 0, v184, vcc
	v_ldexp_f32 v64, v34, v35
	v_or_b32_e32 v34, 0x52, v73
	v_cmp_gt_i32_e32 vcc, v34, v70
	v_sub_u32_e32 v34, v34, v70
	v_sub_u32_e32 v35, 0, v34
	v_max_i32_e32 v34, v34, v35
	v_cvt_f32_u32_e32 v34, v34
	v_cndmask_b32_e32 v35, v78, v75, vcc
	v_mul_f32_e32 v36, v35, v34
	v_cmp_gt_f32_e32 vcc, s69, v36
	s_nop 1
	v_cndmask_b32_e32 v36, 0, v183, vcc
	v_fmac_f32_e32 v36, v35, v34
	v_exp_f32_e32 v34, v36
	v_cndmask_b32_e32 v35, 0, v184, vcc
	v_ldexp_f32 v63, v34, v35
	v_or_b32_e32 v34, 0x53, v73
	v_cmp_gt_i32_e32 vcc, v34, v70
	v_sub_u32_e32 v34, v34, v70
	v_sub_u32_e32 v35, 0, v34
	v_max_i32_e32 v34, v34, v35
	v_cvt_f32_u32_e32 v34, v34
	v_cndmask_b32_e32 v35, v78, v75, vcc
	v_mul_f32_e32 v36, v35, v34
	v_cmp_gt_f32_e32 vcc, s69, v36
	s_nop 1
	v_cndmask_b32_e32 v36, 0, v183, vcc
	v_fmac_f32_e32 v36, v35, v34
	v_exp_f32_e32 v34, v36
	v_cndmask_b32_e32 v35, 0, v184, vcc
	v_cmp_gt_i32_e32 vcc, v39, v70
	v_sub_u32_e32 v39, v39, v70
	v_sub_u32_e32 v40, 0, v39
	v_ldexp_f32 v65, v34, v35
	ds_read_b128 v[34:37], v38 offset:32256
	v_max_i32_e32 v39, v39, v40
	v_cvt_f32_u32_e32 v39, v39
	v_cndmask_b32_e32 v40, v78, v75, vcc
	s_waitcnt lgkmcnt(0)
	v_mfma_f32_16x16x32_bf16 v[34:37], v[34:37], v[6:9], 0
	v_mul_f32_e32 v41, v40, v39
	v_cmp_gt_f32_e32 vcc, s69, v41
	v_mfma_f32_16x16x32_bf16 v[34:37], v[66:69], v[2:5], v[34:37]
	s_nop 0
	v_cndmask_b32_e32 v41, 0, v183, vcc
	v_fmac_f32_e32 v41, v40, v39
	v_exp_f32_e32 v39, v41
	v_cndmask_b32_e32 v40, 0, v184, vcc
	v_ldexp_f32 v66, v39, v40
	v_or_b32_e32 v39, 0x61, v73
	v_cmp_gt_i32_e32 vcc, v39, v70
	v_sub_u32_e32 v39, v39, v70
	v_sub_u32_e32 v40, 0, v39
	v_max_i32_e32 v39, v39, v40
	v_cvt_f32_u32_e32 v39, v39
	v_cndmask_b32_e32 v40, v78, v75, vcc
	v_mul_f32_e32 v41, v40, v39
	v_cmp_gt_f32_e32 vcc, s69, v41
	s_nop 1
	v_cndmask_b32_e32 v41, 0, v183, vcc
	v_fmac_f32_e32 v41, v40, v39
	v_exp_f32_e32 v39, v41
	v_cndmask_b32_e32 v40, 0, v184, vcc
	v_ldexp_f32 v68, v39, v40
	v_or_b32_e32 v39, 0x62, v73
	v_cmp_gt_i32_e32 vcc, v39, v70
	v_sub_u32_e32 v39, v39, v70
	v_sub_u32_e32 v40, 0, v39
	v_max_i32_e32 v39, v39, v40
	v_cvt_f32_u32_e32 v39, v39
	v_cndmask_b32_e32 v40, v78, v75, vcc
	v_mul_f32_e32 v41, v40, v39
	v_cmp_gt_f32_e32 vcc, s69, v41
	s_nop 1
	v_cndmask_b32_e32 v41, 0, v183, vcc
	v_fmac_f32_e32 v41, v40, v39
	v_exp_f32_e32 v39, v41
	v_cndmask_b32_e32 v40, 0, v184, vcc
	v_ldexp_f32 v67, v39, v40
	v_or_b32_e32 v39, 0x63, v73
	v_cmp_gt_i32_e32 vcc, v39, v70
	v_sub_u32_e32 v39, v39, v70
	v_sub_u32_e32 v40, 0, v39
	v_max_i32_e32 v39, v39, v40
	v_cvt_f32_u32_e32 v39, v39
	v_cndmask_b32_e32 v40, v78, v75, vcc
	v_mul_f32_e32 v41, v40, v39
	v_cmp_gt_f32_e32 vcc, s69, v41
	s_nop 1
	v_cndmask_b32_e32 v41, 0, v183, vcc
	v_fmac_f32_e32 v41, v40, v39
	v_cndmask_b32_e32 v40, 0, v184, vcc
	v_cmp_gt_i32_e32 vcc, v74, v70
	v_sub_u32_e32 v74, v74, v70
	v_sub_u32_e32 v76, 0, v74
	v_max_i32_e32 v74, v74, v76
	v_cvt_f32_u32_e32 v74, v74
	v_cndmask_b32_e32 v76, v78, v75, vcc
	v_exp_f32_e32 v39, v41
	v_mul_f32_e32 v77, v76, v74
	v_cmp_gt_f32_e32 vcc, s69, v77
	v_ldexp_f32 v69, v39, v40
	ds_read_b128 v[38:41], v38 offset:34624
	v_cndmask_b32_e32 v77, 0, v183, vcc
	v_fmac_f32_e32 v77, v76, v74
	v_exp_f32_e32 v74, v77
	v_cndmask_b32_e32 v76, 0, v184, vcc
	s_waitcnt lgkmcnt(0)
	v_mfma_f32_16x16x32_bf16 v[38:41], v[38:41], v[2:5], v[80:83]
	v_ldexp_f32 v76, v74, v76
	v_or_b32_e32 v74, 0x71, v73
	v_cmp_gt_i32_e32 vcc, v74, v70
	v_sub_u32_e32 v74, v74, v70
	v_sub_u32_e32 v77, 0, v74
	v_max_i32_e32 v74, v74, v77
	v_cvt_f32_u32_e32 v74, v74
	v_cndmask_b32_e32 v77, v78, v75, vcc
	v_mov_b32_e32 v82, v35
	v_mov_b32_e32 v35, v36
	v_mul_f32_e32 v79, v77, v74
	v_cmp_gt_f32_e32 vcc, s69, v79
	v_mov_b32_e32 v36, v31
	v_mov_b32_e32 v31, v32
	v_cndmask_b32_e32 v79, 0, v183, vcc
	v_fmac_f32_e32 v79, v77, v74
	v_exp_f32_e32 v74, v79
	v_cndmask_b32_e32 v77, 0, v184, vcc
	v_mov_b32_e32 v32, v27
	v_mov_b32_e32 v27, v28
	v_ldexp_f32 v80, v74, v77
	v_or_b32_e32 v74, 0x72, v73
	v_cmp_gt_i32_e32 vcc, v74, v70
	v_sub_u32_e32 v74, v74, v70
	v_sub_u32_e32 v77, 0, v74
	v_max_i32_e32 v74, v74, v77
	v_cvt_f32_u32_e32 v74, v74
	v_cndmask_b32_e32 v77, v78, v75, vcc
	v_or_b32_e32 v73, 0x73, v73
	v_pk_mul_f32 v[58:59], v[58:59], v[26:27]
	v_mul_f32_e32 v79, v77, v74
	v_cmp_gt_f32_e32 vcc, s69, v79
	v_mov_b32_e32 v26, v23
	v_mov_b32_e32 v23, v24
	v_cndmask_b32_e32 v79, 0, v183, vcc
	v_fmac_f32_e32 v79, v77, v74
	v_exp_f32_e32 v74, v79
	v_cndmask_b32_e32 v77, 0, v184, vcc
	v_cmp_gt_i32_e32 vcc, v73, v70
	v_sub_u32_e32 v73, v73, v70
	v_ldexp_f32 v77, v74, v77
	v_sub_u32_e32 v74, 0, v73
	v_mov_b32_e32 v83, v37
	v_mov_b32_e32 v37, v33
	v_mov_b32_e32 v33, v29
	v_pk_mul_f32 v[28:29], v[54:55], v[22:23]
	v_mov_b32_e32 v22, v19
; __device__ __forceinline__ unsigned pk2(float lo, float hi) { return f2bf(lo) | (f2bf(hi) << 16); }
; #define MFMA16(a, b, c) __builtin_amdgcn_mfma_f32_16x16x32_bf16(a, b, c, 0, 0, 0)
; __device__ __forceinline__ void ret2_task(const Params& p_, int l, int task, unsigned char* lds) {
;     ...
;         for (int r = 0; r < 4; ++r) { const int aj = 16 * jt + 4 * fq + r; const float wg = (aj <= ai) ? exp2f(l2f * (float)(ai - aj)) : exp2f(l2b * (float)(aj - ai)); sc[r] = acc[r] * wg; }
;         pp[jt][0] = pk2(sc[0], sc[1]); pp[jt][1] = pk2(sc[2], sc[3]); }
;     const float qdf = exp2f(l2f * (float)(ai + 1)), qdb = exp2f(l2b * (float)(128 - ai));
;     f32x4 tot[4]; float ss = 0.f;
; #pragma unroll
;     for (int et = 0; et < 4; ++et) { f32x4 o = {0.f, 0.f, 0.f, 0.f}, cfa = o, cba = o;
; #pragma unroll
;         for (int t = 0; t < 4; ++t) { const u32x2 vlo = *(const u32x2*)(VT + (16 * et + fr) * 136 + 32 * t + 4 * fq), vhi = *(const u32x2*)(VT + (16 * et + fr) * 136 + 32 * t + 16 + 4 * fq);
;             o = MFMA16(mk8(vlo.x, vlo.y, vhi.x, vhi.y), mk8(pp[2 * t][0], pp[2 * t][1], pp[2 * t + 1][0], pp[2 * t + 1][1]), o); }
; #pragma unroll
;         for (int ks = 0; ks < 2; ++ks) { const bf16x8v sf = *(const bf16x8v*)(STF + (16 * et + fr) * 72 + 32 * ks + 8 * fq), sb = *(const bf16x8v*)(STB + (16 * et + fr) * 72 + 32 * ks + 8 * fq);
;             cfa = MFMA16(sf, qf[ks], cfa); cba = MFMA16(sb, qf[ks], cba); }
	v_mov_b32_e32 v19, v20
	v_max_i32_e32 v73, v73, v74
	v_pk_mul_f32 v[50:51], v[50:51], v[18:19]
	v_mov_b32_e32 v18, v15
	v_mov_b32_e32 v15, v16
	v_cvt_f32_u32_e32 v73, v73
	v_mov_b32_e32 v23, v21
	v_pk_mul_f32 v[20:21], v[46:47], v[14:15]
	v_mov_b32_e32 v14, v11
	v_mov_b32_e32 v15, v13
	v_mov_b32_e32 v11, v12
	v_mov_b32_e32 v12, v38
	v_mov_b32_e32 v13, v40
	v_pk_mul_f32 v[10:11], v[42:43], v[10:11]
	v_pk_mul_f32 v[42:43], v[76:77], v[12:13]
	v_add_u32_e32 v12, 1, v70
	v_cvt_f32_i32_e32 v12, v12
	v_cndmask_b32_e32 v74, v78, v75, vcc
	v_mul_f32_e32 v79, v74, v73
	v_cmp_gt_f32_e32 vcc, s69, v79
	v_mul_f32_e32 v13, v78, v12
	v_mov_b32_e32 v40, v39
	v_cndmask_b32_e32 v79, 0, v183, vcc
	v_fmac_f32_e32 v79, v74, v73
	v_cndmask_b32_e32 v74, 0, v184, vcc
	v_cmp_gt_f32_e32 vcc, s69, v13
	v_exp_f32_e32 v73, v79
	v_pk_mul_f32 v[52:53], v[52:53], v[22:23]
	v_cndmask_b32_e32 v13, 0, v183, vcc
	v_fmac_f32_e32 v13, v78, v12
	v_exp_f32_e32 v12, v13
	v_cndmask_b32_e32 v13, 0, v184, vcc
	v_ldexp_f32 v81, v73, v74
	v_pk_mul_f32 v[22:23], v[44:45], v[14:15]
	v_ldexp_f32 v38, v12, v13
	v_sub_u32_e32 v12, 0x80, v70
	v_cvt_f32_i32_e32 v12, v12
	v_pk_mul_f32 v[44:45], v[80:81], v[40:41]
	v_mov_b32_e32 v19, v17
	v_pk_mul_f32 v[18:19], v[48:49], v[18:19]
	v_mul_f32_e32 v13, v75, v12
	v_cmp_gt_f32_e32 vcc, s69, v13
	v_mov_b32_e32 v27, v25
	v_bfe_u32 v24, v23, 16, 1
	v_cndmask_b32_e32 v13, 0, v183, vcc
	v_fmac_f32_e32 v13, v75, v12
	v_exp_f32_e32 v12, v13
	v_cndmask_b32_e32 v13, 0, v184, vcc
	v_bfe_u32 v25, v22, 16, 1
	v_add3_u32 v22, v22, v25, s14
	v_ldexp_f32 v40, v12, v13
	v_mul_u32_u24_e32 v12, 0x110, v71
	v_add3_u32 v39, 0, v12, v0
	v_add_u32_e32 v41, 0x9000, v39
	ds_read2_b64 v[14:17], v41 offset1:4
	v_bfe_u32 v12, v19, 16, 1
	v_bfe_u32 v13, v18, 16, 1
	v_add3_u32 v18, v18, v13, s14
	v_add3_u32 v12, v19, v12, s14
	v_bfe_u32 v13, v10, 16, 1
	v_bfe_u32 v19, v11, 16, 1
	v_add3_u32 v11, v11, v19, s14
	v_add3_u32 v10, v10, v13, s14
	v_add3_u32 v23, v23, v24, s14
	v_bfe_u32 v24, v20, 16, 1
	v_bfe_u32 v25, v21, 16, 1
	v_lshrrev_b32_e32 v10, 16, v10
	v_lshrrev_b32_e32 v11, 16, v11
	v_add3_u32 v21, v21, v25, s14
	v_add3_u32 v20, v20, v24, s14
	v_and_or_b32 v11, v23, s15, v11
	v_and_or_b32 v10, v22, s15, v10
	ds_read2_b64 v[22:25], v41 offset0:8 offset1:12
	v_lshrrev_b32_e32 v19, 16, v20
	v_lshrrev_b32_e32 v13, 16, v21
	v_pk_mul_f32 v[26:27], v[56:57], v[26:27]
	v_and_or_b32 v13, v12, s15, v13
	v_and_or_b32 v12, v18, s15, v19
	v_pk_mul_f32 v[36:37], v[64:65], v[36:37]
	v_pk_mul_f32 v[32:33], v[60:61], v[32:33]
	s_waitcnt lgkmcnt(1)
	v_mfma_f32_16x16x32_bf16 v[18:21], v[14:17], v[10:13], 0
	v_bfe_u32 v14, v27, 16, 1
	v_bfe_u32 v15, v26, 16, 1
	v_bfe_u32 v16, v53, 16, 1
	v_bfe_u32 v17, v52, 16, 1
	v_add3_u32 v46, v52, v17, s14
	v_add3_u32 v47, v53, v16, s14
	v_add3_u32 v15, v26, v15, s14
	v_add3_u32 v14, v27, v14, s14
	v_bfe_u32 v16, v50, 16, 1
	v_bfe_u32 v17, v51, 16, 1
	v_bfe_u32 v26, v28, 16, 1
	v_bfe_u32 v27, v29, 16, 1
	v_add3_u32 v27, v29, v27, s14
	v_add3_u32 v26, v28, v26, s14
	v_add3_u32 v17, v51, v17, s14
	v_add3_u32 v16, v50, v16, s14
	v_lshrrev_b32_e32 v28, 16, v16
	v_lshrrev_b32_e32 v29, 16, v17
	v_lshrrev_b32_e32 v16, 16, v26
	v_lshrrev_b32_e32 v17, 16, v27
	v_and_or_b32 v17, v14, s15, v17
	v_and_or_b32 v16, v15, s15, v16
	v_and_or_b32 v15, v47, s15, v29
	v_and_or_b32 v14, v46, s15, v28
	ds_read2_b64 v[26:29], v41 offset0:16 offset1:20
	v_pk_mul_f32 v[30:31], v[62:63], v[30:31]
	s_waitcnt lgkmcnt(1)
	v_mfma_f32_16x16x32_bf16 v[18:21], v[22:25], v[14:17], v[18:21]
	v_bfe_u32 v22, v37, 16, 1
	v_bfe_u32 v23, v36, 16, 1
	v_bfe_u32 v24, v33, 16, 1
	v_bfe_u32 v25, v32, 16, 1
	v_add3_u32 v32, v32, v25, s14
	v_add3_u32 v33, v33, v24, s14
	v_add3_u32 v23, v36, v23, s14
	v_add3_u32 v22, v37, v22, s14
	v_bfe_u32 v24, v58, 16, 1
	v_bfe_u32 v25, v59, 16, 1
	v_bfe_u32 v36, v30, 16, 1
	v_bfe_u32 v37, v31, 16, 1
	v_add3_u32 v31, v31, v37, s14
	v_add3_u32 v30, v30, v36, s14
	v_add3_u32 v25, v59, v25, s14
	v_add3_u32 v24, v58, v24, s14
	v_lshrrev_b32_e32 v36, 16, v24
	v_lshrrev_b32_e32 v37, 16, v25
	v_lshrrev_b32_e32 v24, 16, v30
	v_lshrrev_b32_e32 v25, 16, v31
	v_and_or_b32 v25, v22, s15, v25
	v_and_or_b32 v24, v23, s15, v24
	v_and_or_b32 v23, v33, s15, v37
	v_and_or_b32 v22, v32, s15, v36
	ds_read2_b64 v[30:33], v41 offset0:24 offset1:28
	v_pk_mul_f32 v[68:69], v[68:69], v[82:83]
	v_pk_mul_f32 v[34:35], v[66:67], v[34:35]
	s_waitcnt lgkmcnt(1)
	v_mfma_f32_16x16x32_bf16 v[26:29], v[26:29], v[22:25], v[18:21]
	v_bfe_u32 v41, v42, 16, 1
	v_add3_u32 v41, v42, v41, s14
	v_add_u32_e32 v47, 0xb000, v39
	v_bfe_u32 v19, v44, 16, 1
	v_bfe_u32 v20, v69, 16, 1
	v_bfe_u32 v21, v68, 16, 1
	v_add3_u32 v36, v68, v21, s14
	v_add3_u32 v37, v69, v20, s14
	v_add3_u32 v19, v44, v19, s14
	v_bfe_u32 v20, v34, 16, 1
	v_bfe_u32 v21, v35, 16, 1
	v_bfe_u32 v44, v43, 16, 1
	v_bfe_u32 v18, v45, 16, 1
	v_add3_u32 v43, v43, v44, s14
	v_add3_u32 v21, v35, v21, s14
	v_add3_u32 v20, v34, v20, s14
	v_add3_u32 v18, v45, v18, s14
	v_lshrrev_b32_e32 v34, 16, v20
	v_lshrrev_b32_e32 v35, 16, v21
	v_lshrrev_b32_e32 v20, 16, v41
	v_lshrrev_b32_e32 v21, 16, v43
	v_and_or_b32 v21, v18, s15, v21
	v_and_or_b32 v20, v19, s15, v20
	v_and_or_b32 v19, v37, s15, v35
	v_and_or_b32 v18, v36, s15, v34
	s_waitcnt lgkmcnt(0)
	s_nop 0
	v_mfma_f32_16x16x32_bf16 v[26:29], v[30:33], v[18:21], v[26:29]
	v_mul_u32_u24_e32 v30, 0x48, v71
	v_lshlrev_b32_e32 v30, 1, v30
	v_add3_u32 v41, s6, v72, v30
	v_add3_u32 v46, s24, v72, v30
	ds_read_b128 v[30:33], v41
	ds_read_b128 v[34:37], v46
	s_waitcnt lgkmcnt(1)
	v_mfma_f32_16x16x32_bf16 v[30:33], v[30:33], v[6:9], 0
	ds_read_b128 v[42:45], v41 offset:64
	ds_read_b128 v[48:51], v46 offset:64
	s_or_b32 s6, s43, s42
	s_lshl_b32 s24, s44, 1
	s_waitcnt lgkmcnt(2)
; #define MFMA16(a, b, c) __builtin_amdgcn_mfma_f32_16x16x32_bf16(a, b, c, 0, 0, 0)
; __device__ __forceinline__ void ret2_task(const Params& p_, int l, int task, unsigned char* lds) {
;     ...
; #pragma unroll
;     for (int et = 0; et < 4; ++et) { f32x4 o = {0.f, 0.f, 0.f, 0.f}, cfa = o, cba = o;
; #pragma unroll
;         for (int t = 0; t < 4; ++t) { const u32x2 vlo = *(const u32x2*)(VT + (16 * et + fr) * 136 + 32 * t + 4 * fq), vhi = *(const u32x2*)(VT + (16 * et + fr) * 136 + 32 * t + 16 + 4 * fq);
;             o = MFMA16(mk8(vlo.x, vlo.y, vhi.x, vhi.y), mk8(pp[2 * t][0], pp[2 * t][1], pp[2 * t + 1][0], pp[2 * t + 1][1]), o); }
; #pragma unroll
;         for (int ks = 0; ks < 2; ++ks) { const bf16x8v sf = *(const bf16x8v*)(STF + (16 * et + fr) * 72 + 32 * ks + 8 * fq), sb = *(const bf16x8v*)(STB + (16 * et + fr) * 72 + 32 * ks + 8 * fq);
;             cfa = MFMA16(sf, qf[ks], cfa); cba = MFMA16(sb, qf[ks], cba); }
;         tot[et] = o + cfa * qdf + cba * qdb;
;         ss += (tot[et][0] * tot[et][0] + tot[et][1] * tot[et][1]) + (tot[et][2] * tot[et][2] + tot[et][3] * tot[et][3]); }
;     ss += __shfl_xor(ss, 16); ss += __shfl_xor(ss, 32);
	v_mfma_f32_16x16x32_bf16 v[34:37], v[34:37], v[6:9], 0
	s_cmpk_lt_i32 s10, 0x200
	s_waitcnt lgkmcnt(1)
	v_mfma_f32_16x16x32_bf16 v[30:33], v[42:45], v[2:5], v[30:33]
	s_waitcnt lgkmcnt(0)
	v_mfma_f32_16x16x32_bf16 v[42:45], v[48:51], v[2:5], v[34:37]
	s_nop 5
	v_fma_f32 v28, v38, v32, v28
	v_fma_f32 v29, v38, v33, v29
	v_pk_fma_f32 v[26:27], v[38:39], v[30:31], v[26:27] op_sel_hi:[0,1,1]
	v_pk_fma_f32 v[34:35], v[40:41], v[44:45], v[28:29] op_sel_hi:[0,1,1]
	v_pk_fma_f32 v[36:37], v[40:41], v[42:43], v[26:27] op_sel_hi:[0,1,1]
	v_pk_mul_f32 v[26:27], v[34:35], v[34:35]
	v_pk_mul_f32 v[28:29], v[36:37], v[36:37]
	v_add_u32_e32 v44, 0xa000, v39
	v_pk_mov_b32 v[30:31], v[28:29], v[26:27] op_sel:[1,0]
	v_mov_b32_e32 v29, v27
	v_pk_add_f32 v[42:43], v[30:31], v[28:29]
	ds_read2_b64 v[26:29], v44 offset0:32 offset1:36
	ds_read2_b64 v[30:33], v44 offset0:40 offset1:44
	s_waitcnt lgkmcnt(1)
	v_mfma_f32_16x16x32_bf16 v[26:29], v[26:29], v[10:13], 0
	s_waitcnt lgkmcnt(0)
	v_mfma_f32_16x16x32_bf16 v[26:29], v[30:33], v[14:17], v[26:29]
	ds_read2_b64 v[30:33], v44 offset0:48 offset1:52
	s_waitcnt lgkmcnt(0)
	v_mfma_f32_16x16x32_bf16 v[26:29], v[30:33], v[22:25], v[26:29]
	ds_read2_b64 v[30:33], v44 offset0:56 offset1:60
	s_waitcnt lgkmcnt(0)
	v_mfma_f32_16x16x32_bf16 v[26:29], v[30:33], v[18:21], v[26:29]
	ds_read_b128 v[30:33], v41 offset:2304
	ds_read_b128 v[48:51], v46 offset:2304
	ds_read_b128 v[52:55], v41 offset:2368
	ds_read_b128 v[56:59], v46 offset:2368
	s_waitcnt lgkmcnt(3)
	v_mfma_f32_16x16x32_bf16 v[30:33], v[30:33], v[6:9], 0
	s_waitcnt lgkmcnt(2)
	v_mfma_f32_16x16x32_bf16 v[48:51], v[48:51], v[6:9], 0
	s_waitcnt lgkmcnt(1)
	v_mfma_f32_16x16x32_bf16 v[30:33], v[52:55], v[2:5], v[30:33]
	s_waitcnt lgkmcnt(0)
	v_mfma_f32_16x16x32_bf16 v[48:51], v[56:59], v[2:5], v[48:51]
	s_nop 5
	v_fma_f32 v28, v38, v32, v28
	v_fma_f32 v29, v38, v33, v29
	v_pk_fma_f32 v[26:27], v[38:39], v[30:31], v[26:27] op_sel_hi:[0,1,1]
	v_pk_fma_f32 v[30:31], v[40:41], v[50:51], v[28:29] op_sel_hi:[0,1,1]
	v_pk_fma_f32 v[32:33], v[40:41], v[48:49], v[26:27] op_sel_hi:[0,1,1]
	v_pk_mul_f32 v[26:27], v[30:31], v[30:31]
	v_pk_mul_f32 v[28:29], v[32:33], v[32:33]
	ds_read2_b64 v[48:51], v47 offset0:72 offset1:76
	v_pk_mov_b32 v[44:45], v[28:29], v[26:27] op_sel:[1,0]
	v_mov_b32_e32 v29, v27
	v_pk_add_f32 v[44:45], v[44:45], v[28:29]
	ds_read2_b64 v[26:29], v47 offset0:64 offset1:68
	s_waitcnt lgkmcnt(0)
	v_mfma_f32_16x16x32_bf16 v[26:29], v[26:29], v[10:13], 0
	v_mfma_f32_16x16x32_bf16 v[26:29], v[48:51], v[14:17], v[26:29]
	ds_read2_b64 v[48:51], v47 offset0:80 offset1:84
	s_waitcnt lgkmcnt(0)
	v_mfma_f32_16x16x32_bf16 v[26:29], v[48:51], v[22:25], v[26:29]
	ds_read2_b64 v[48:51], v47 offset0:88 offset1:92
	s_waitcnt lgkmcnt(0)
	v_mfma_f32_16x16x32_bf16 v[26:29], v[48:51], v[18:21], v[26:29]
	ds_read_b128 v[48:51], v41 offset:4608
	ds_read_b128 v[52:55], v46 offset:4608
	ds_read_b128 v[56:59], v41 offset:4672
	ds_read_b128 v[60:63], v46 offset:4672
	s_waitcnt lgkmcnt(3)
	v_mfma_f32_16x16x32_bf16 v[48:51], v[48:51], v[6:9], 0
	s_waitcnt lgkmcnt(2)
	v_mfma_f32_16x16x32_bf16 v[52:55], v[52:55], v[6:9], 0
	s_waitcnt lgkmcnt(1)
	v_mfma_f32_16x16x32_bf16 v[48:51], v[56:59], v[2:5], v[48:51]
	s_waitcnt lgkmcnt(0)
	v_mfma_f32_16x16x32_bf16 v[52:55], v[60:63], v[2:5], v[52:55]
	s_nop 5
	v_fma_f32 v28, v38, v50, v28
	v_fma_f32 v29, v38, v51, v29
	v_pk_fma_f32 v[48:49], v[38:39], v[48:49], v[26:27] op_sel_hi:[0,1,1]
	v_add_u32_e32 v39, 0xc000, v39
	v_pk_fma_f32 v[26:27], v[40:41], v[54:55], v[28:29] op_sel_hi:[0,1,1]
	v_pk_fma_f32 v[28:29], v[40:41], v[52:53], v[48:49] op_sel_hi:[0,1,1]
	ds_read2_b64 v[48:51], v39 offset0:96 offset1:100
	s_waitcnt lgkmcnt(0)
	v_mfma_f32_16x16x32_bf16 v[10:13], v[48:51], v[10:13], 0
	ds_read2_b64 v[48:51], v39 offset0:104 offset1:108
	s_waitcnt lgkmcnt(0)
	v_mfma_f32_16x16x32_bf16 v[10:13], v[48:51], v[14:17], v[10:13]
	ds_read2_b64 v[14:17], v39 offset0:112 offset1:116
	s_waitcnt lgkmcnt(0)
	v_mfma_f32_16x16x32_bf16 v[10:13], v[14:17], v[22:25], v[10:13]
	ds_read2_b64 v[14:17], v39 offset0:120 offset1:124
	s_waitcnt lgkmcnt(0)
	v_mfma_f32_16x16x32_bf16 v[10:13], v[14:17], v[18:21], v[10:13]
	ds_read_b128 v[14:17], v41 offset:6912
	ds_read_b128 v[18:21], v46 offset:6912
	s_waitcnt lgkmcnt(1)
	v_mfma_f32_16x16x32_bf16 v[14:17], v[14:17], v[6:9], 0
	s_waitcnt lgkmcnt(0)
	v_mfma_f32_16x16x32_bf16 v[6:9], v[18:21], v[6:9], 0
	ds_read_b128 v[18:21], v41 offset:6976
	ds_read_b128 v[22:25], v46 offset:6976
	s_waitcnt lgkmcnt(1)
	v_mfma_f32_16x16x32_bf16 v[14:17], v[18:21], v[2:5], v[14:17]
	v_mov_b32_e32 v18, v36
	v_mov_b32_e32 v19, v34
	v_mov_b32_e32 v34, v37
	s_waitcnt lgkmcnt(0)
	v_mfma_f32_16x16x32_bf16 v[4:7], v[22:25], v[2:5], v[6:9]
	s_nop 2
	v_fma_f32 v2, v38, v16, v12
	v_fma_f32 v3, v38, v17, v13
	v_pk_fma_f32 v[8:9], v[38:39], v[14:15], v[10:11] op_sel_hi:[0,1,1]
	s_nop 1
	v_pk_fma_f32 v[4:5], v[40:41], v[4:5], v[8:9] op_sel_hi:[0,1,1]
	v_pk_fma_f32 v[2:3], v[40:41], v[6:7], v[2:3] op_sel_hi:[0,1,1]
	v_mul_f32_e32 v8, v4, v4
	v_pk_add_f32 v[6:7], v[42:43], v[42:43] op_sel:[0,1] op_sel_hi:[1,0]
	v_mul_f32_e32 v10, v5, v5
	v_mov_b32_e32 v7, v8
	v_pk_add_f32 v[8:9], v[44:45], v[44:45] op_sel:[0,1] op_sel_hi:[1,0]
	v_mul_f32_e32 v11, v2, v2
	v_mov_b32_e32 v9, v10
	v_pk_add_f32 v[6:7], v[6:7], v[8:9]
	v_mul_f32_e32 v8, v29, v29
	v_pk_fma_f32 v[8:9], v[28:29], v[28:29], v[8:9] op_sel_hi:[1,1,0]
	v_mul_f32_e32 v10, v27, v27
	v_mul_f32_e32 v12, v3, v3
	v_mov_b32_e32 v9, v11
	v_pk_fma_f32 v[10:11], v[26:27], v[26:27], v[10:11] op_sel_hi:[1,1,0]
	s_nop 0
	v_mov_b32_e32 v11, v12
	v_pk_add_f32 v[8:9], v[8:9], v[10:11]
	s_nop 0
	v_pk_add_f32 v[6:7], v[6:7], v[8:9]
	v_and_b32_e32 v8, 64, v178
	v_add_f32_e32 v6, v6, v7
	v_xor_b32_e32 v7, 16, v178
	v_add_u32_e32 v8, 64, v8
	v_cmp_lt_i32_e32 vcc, v7, v8
	s_nop 1
	v_cndmask_b32_e32 v7, v178, v7, vcc
	v_lshlrev_b32_e32 v7, 2, v7
	ds_bpermute_b32 v7, v7, v6
	s_waitcnt lgkmcnt(0)
; __device__ __forceinline__ unsigned pk2(float lo, float hi) { return f2bf(lo) | (f2bf(hi) << 16); }
; __device__ __forceinline__ float bflo(unsigned u) { return __uint_as_float(u << 16); }
; __device__ __forceinline__ float bfhi(unsigned u) { return __uint_as_float(u & 0xffff0000u); }
; __device__ __forceinline__ float silu_f(float v) { return v / (1.f + __expf(-v)); }
; __device__ __forceinline__ void ret2_task(const Params& p_, int l, int task, unsigned char* lds) {
;     ...
;     ss += __shfl_xor(ss, 16); ss += __shfl_xor(ss, 32);
;     const float rs = rsqrtf(ss * (1.f / 64.f) + 1e-6f);
;     const size_t tok = (size_t)b * SEQ + n * 128 + ai;
;     const bf16* Z = (const bf16*)(p.ws + WS_Z); bf16* CAT = (bf16*)(p.ws + WS_CAT);
; #pragma unroll
;     for (int et = 0; et < 4; ++et) { const u32x2 gz = *(const u32x2*)(Z + tok * DIN + 9 * DG + h * 64 + 16 * et + 4 * fq); u32x2 o;
;         o.x = pk2(tot[et][0] * rs * silu_f(bflo(gz.x)), tot[et][1] * rs * silu_f(bfhi(gz.x))); o.y = pk2(tot[et][2] * rs * silu_f(bflo(gz.y)), tot[et][3] * rs * silu_f(bfhi(gz.y)));
;         *(u32x2*)(CAT + tok * DM + 1024 + h * 64 + 16 * et + 4 * fq) = o; }
	v_add_f32_e32 v6, v6, v7
	v_xor_b32_e32 v7, 32, v178
	v_cmp_lt_i32_e32 vcc, v7, v8
	v_mov_b64_e32 v[8:9], s[36:37]
	s_nop 0
	v_cndmask_b32_e32 v7, v178, v7, vcc
	v_lshlrev_b32_e32 v7, 2, v7
	ds_bpermute_b32 v7, v7, v6
	s_waitcnt lgkmcnt(0)
	v_add_f32_e32 v6, v6, v7
	v_fmamk_f32 v6, v6, 0x3c800000, v146
	v_cmp_gt_f32_e32 vcc, s92, v6
	v_mul_f32_e32 v7, 0x4b800000, v6
	s_nop 0
	v_cndmask_b32_e32 v6, v6, v7, vcc
	v_rsq_f32_e32 v6, v6
	s_nop 0
	v_mul_f32_e32 v7, 0x45800000, v6
	v_cndmask_b32_e32 v6, v6, v7, vcc
	v_add_u32_e32 v7, s6, v70
	v_mad_i64_i32 v[8:9], s[12:13], v7, s75, v[8:9]
	v_lshl_add_u64 v[10:11], v[8:9], 0, s[24:25]
	v_lshl_add_u64 v[12:13], v[10:11], 0, v[0:1]
	s_mov_b64 s[12:13], 0xad22400
	s_movk_i32 s6, 0xdc00
	v_lshl_add_u64 v[10:11], v[12:13], 0, s[12:13]
	v_mad_i64_i32 v[8:9], s[12:13], v7, s6, v[8:9]
	s_mov_b32 s6, 0xad22000
	v_add_co_u32_e32 v12, vcc, s6, v12
	v_lshl_add_u64 v[8:9], v[8:9], 0, s[24:25]
	s_nop 0
	v_addc_co_u32_e32 v13, vcc, 0, v13, vcc
	global_load_dwordx2 v[84:85], v[10:11], off offset:32
	global_load_dwordx2 v[86:87], v[10:11], off offset:64
	global_load_dwordx2 v[88:89], v[10:11], off offset:96
	global_load_dwordx2 v[12:13], v[12:13], off offset:1024
	v_lshl_add_u64 v[14:15], v[8:9], 0, v[0:1]
	s_mov_b64 s[12:13], 0x12d20800
	v_lshl_add_u64 v[8:9], v[14:15], 0, s[12:13]
	s_mov_b32 s6, 0x12d20000
	s_waitcnt vmcnt(0)
	v_lshlrev_b32_e32 v0, 16, v13
	v_lshlrev_b32_e32 v7, 16, v12
	v_mul_f32_e32 v16, 0xbfb8aa3b, v7
	v_and_b32_e32 v20, 0xffff0000, v13
	v_mul_f32_e32 v13, 0xbfb8aa3b, v0
	v_exp_f32_e32 v16, v16
	v_exp_f32_e32 v17, v13
	v_and_b32_e32 v21, 0xffff0000, v12
	v_mul_f32_e32 v12, 0xbfb8aa3b, v21
	v_exp_f32_e32 v12, v12
	v_pk_add_f32 v[16:17], v[16:17], 1.0 op_sel_hi:[1,0]
	v_pk_mul_f32 v[18:19], v[18:19], v[6:7] op_sel_hi:[1,0]
	v_div_scale_f32 v13, s[12:13], v17, v17, v0
	v_rcp_f32_e32 v22, v13
	s_nop 0
	v_fma_f32 v23, -v13, v22, 1.0
	v_fmac_f32_e32 v22, v23, v22
	v_div_scale_f32 v23, vcc, v0, v17, v0
	v_mul_f32_e32 v24, v23, v22
	v_fma_f32 v25, -v13, v24, v23
	v_fmac_f32_e32 v24, v25, v22
	v_fma_f32 v13, -v13, v24, v23
	v_div_fmas_f32 v13, v13, v22, v24
	v_div_fixup_f32 v17, v13, v17, v0
	v_div_scale_f32 v0, s[12:13], v16, v16, v7
	v_rcp_f32_e32 v13, v0
	s_nop 0
	v_fma_f32 v22, -v0, v13, 1.0
	v_fmac_f32_e32 v13, v22, v13
	v_div_scale_f32 v22, vcc, v7, v16, v7
	v_mul_f32_e32 v23, v22, v13
	v_fma_f32 v24, -v0, v23, v22
	v_fmac_f32_e32 v23, v24, v13
	v_fma_f32 v0, -v0, v23, v22
	v_div_fmas_f32 v0, v0, v13, v23
	v_div_fixup_f32 v16, v0, v16, v7
	v_mul_f32_e32 v0, 0xbfb8aa3b, v20
	v_exp_f32_e32 v13, v0
	v_pk_mul_f32 v[16:17], v[16:17], v[18:19]
	v_pk_mul_f32 v[18:19], v[34:35], v[6:7] op_sel_hi:[1,0]
	v_pk_add_f32 v[12:13], v[12:13], 1.0 op_sel_hi:[1,0]
	s_nop 0
	v_div_scale_f32 v0, s[12:13], v13, v13, v20
	v_rcp_f32_e32 v7, v0
	s_nop 0
	v_fma_f32 v22, -v0, v7, 1.0
	v_fmac_f32_e32 v7, v22, v7
	v_div_scale_f32 v22, vcc, v20, v13, v20
	v_mul_f32_e32 v23, v22, v7
	v_fma_f32 v24, -v0, v23, v22
	v_fmac_f32_e32 v23, v24, v7
	v_fma_f32 v0, -v0, v23, v22
	v_div_fmas_f32 v0, v0, v7, v23
	v_div_fixup_f32 v13, v0, v13, v20
	v_div_scale_f32 v0, s[12:13], v12, v12, v21
	v_rcp_f32_e32 v7, v0
	s_nop 0
	v_fma_f32 v20, -v0, v7, 1.0
	v_fmac_f32_e32 v7, v20, v7
	v_div_scale_f32 v20, vcc, v21, v12, v21
	v_mul_f32_e32 v22, v20, v7
	v_fma_f32 v23, -v0, v22, v20
	v_fmac_f32_e32 v22, v23, v7
	v_fma_f32 v0, -v0, v22, v20
	v_div_fmas_f32 v0, v0, v7, v22
	v_div_fixup_f32 v12, v0, v12, v21
	v_pk_mul_f32 v[12:13], v[12:13], v[18:19]
	v_and_b32_sdwa v0, v17, v179 dst_sel:DWORD dst_unused:UNUSED_PAD src0_sel:WORD_1 src1_sel:DWORD
	v_and_b32_sdwa v7, v16, v179 dst_sel:DWORD dst_unused:UNUSED_PAD src0_sel:WORD_1 src1_sel:DWORD
	v_add3_u32 v7, v16, v7, s14
	v_add3_u32 v0, v17, v0, s14
	v_and_b32_sdwa v16, v13, v179 dst_sel:DWORD dst_unused:UNUSED_PAD src0_sel:WORD_1 src1_sel:DWORD
	v_and_b32_sdwa v17, v12, v179 dst_sel:DWORD dst_unused:UNUSED_PAD src0_sel:WORD_1 src1_sel:DWORD
	v_add3_u32 v13, v13, v16, s14
	v_add3_u32 v12, v12, v17, s14
	v_and_b32_e32 v13, 0xffff0000, v13
	v_and_b32_e32 v12, 0xffff0000, v12
	v_add_co_u32_e32 v14, vcc, s6, v14
	v_or_b32_sdwa v13, v13, v0 dst_sel:DWORD dst_unused:UNUSED_PAD src0_sel:DWORD src1_sel:WORD_1
	v_or_b32_sdwa v12, v12, v7 dst_sel:DWORD dst_unused:UNUSED_PAD src0_sel:DWORD src1_sel:WORD_1
	v_addc_co_u32_e32 v15, vcc, 0, v15, vcc
	global_store_dwordx2 v[14:15], v[12:13], off offset:2048
	v_mov_b64_e32 v[12:13], v[84:85]
	v_mov_b32_e32 v16, v32
	v_mov_b32_e32 v17, v30
	v_mov_b32_e32 v30, v33
	s_nop 0
	v_lshlrev_b32_e32 v0, 16, v13
	v_lshlrev_b32_e32 v7, 16, v12
	v_mul_f32_e32 v14, 0xbfb8aa3b, v7
	v_and_b32_e32 v18, 0xffff0000, v13
	v_mul_f32_e32 v13, 0xbfb8aa3b, v0
	v_exp_f32_e32 v14, v14
	v_exp_f32_e32 v15, v13
	v_and_b32_e32 v19, 0xffff0000, v12
	v_mul_f32_e32 v12, 0xbfb8aa3b, v19
	v_exp_f32_e32 v12, v12
	v_pk_add_f32 v[14:15], v[14:15], 1.0 op_sel_hi:[1,0]
	v_pk_mul_f32 v[16:17], v[16:17], v[6:7] op_sel_hi:[1,0]
	v_div_scale_f32 v13, s[12:13], v15, v15, v0
	v_rcp_f32_e32 v20, v13
	s_nop 0
	v_fma_f32 v21, -v13, v20, 1.0
	v_fmac_f32_e32 v20, v21, v20
	v_div_scale_f32 v21, vcc, v0, v15, v0
	v_mul_f32_e32 v22, v21, v20
	v_fma_f32 v23, -v13, v22, v21
	v_fmac_f32_e32 v22, v23, v20
	v_fma_f32 v13, -v13, v22, v21
	v_div_fmas_f32 v13, v13, v20, v22
	v_div_fixup_f32 v15, v13, v15, v0
	v_div_scale_f32 v0, s[12:13], v14, v14, v7
	v_rcp_f32_e32 v13, v0
	s_nop 0
	v_fma_f32 v20, -v0, v13, 1.0
	v_fmac_f32_e32 v13, v20, v13
	v_div_scale_f32 v20, vcc, v7, v14, v7
	v_mul_f32_e32 v21, v20, v13
	v_fma_f32 v22, -v0, v21, v20
	v_fmac_f32_e32 v21, v22, v13
	v_fma_f32 v0, -v0, v21, v20
	v_div_fmas_f32 v0, v0, v13, v21
; __device__ __forceinline__ unsigned pk2(float lo, float hi) { return f2bf(lo) | (f2bf(hi) << 16); }
; __device__ __forceinline__ float bflo(unsigned u) { return __uint_as_float(u << 16); }
; __device__ __forceinline__ float bfhi(unsigned u) { return __uint_as_float(u & 0xffff0000u); }
; __device__ __forceinline__ float silu_f(float v) { return v / (1.f + __expf(-v)); }
; __device__ __forceinline__ void ret2_task(const Params& p_, int l, int task, unsigned char* lds) {
;     ...
;     for (int et = 0; et < 4; ++et) { const u32x2 gz = *(const u32x2*)(Z + tok * DIN + 9 * DG + h * 64 + 16 * et + 4 * fq); u32x2 o;
;         o.x = pk2(tot[et][0] * rs * silu_f(bflo(gz.x)), tot[et][1] * rs * silu_f(bfhi(gz.x))); o.y = pk2(tot[et][2] * rs * silu_f(bflo(gz.y)), tot[et][3] * rs * silu_f(bfhi(gz.y)));
;         *(u32x2*)(CAT + tok * DM + 1024 + h * 64 + 16 * et + 4 * fq) = o; }
	v_div_fixup_f32 v14, v0, v14, v7
	v_mul_f32_e32 v0, 0xbfb8aa3b, v18
	v_exp_f32_e32 v13, v0
	v_pk_mul_f32 v[14:15], v[14:15], v[16:17]
	v_pk_mul_f32 v[16:17], v[30:31], v[6:7] op_sel_hi:[1,0]
	v_pk_add_f32 v[12:13], v[12:13], 1.0 op_sel_hi:[1,0]
	s_nop 0
	v_div_scale_f32 v0, s[12:13], v13, v13, v18
	v_rcp_f32_e32 v7, v0
	s_nop 0
	v_fma_f32 v20, -v0, v7, 1.0
	v_fmac_f32_e32 v7, v20, v7
	v_div_scale_f32 v20, vcc, v18, v13, v18
	v_mul_f32_e32 v21, v20, v7
	v_fma_f32 v22, -v0, v21, v20
	v_fmac_f32_e32 v21, v22, v7
	v_fma_f32 v0, -v0, v21, v20
	v_div_fmas_f32 v0, v0, v7, v21
	v_div_fixup_f32 v13, v0, v13, v18
	v_div_scale_f32 v0, s[12:13], v12, v12, v19
	v_rcp_f32_e32 v7, v0
	s_nop 0
	v_fma_f32 v18, -v0, v7, 1.0
	v_fmac_f32_e32 v7, v18, v7
	v_div_scale_f32 v18, vcc, v19, v12, v19
	v_mul_f32_e32 v20, v18, v7
	v_fma_f32 v21, -v0, v20, v18
	v_fmac_f32_e32 v20, v21, v7
	v_fma_f32 v0, -v0, v20, v18
	v_div_fmas_f32 v0, v0, v7, v20
	v_div_fixup_f32 v12, v0, v12, v19
	v_pk_mul_f32 v[12:13], v[12:13], v[16:17]
	v_and_b32_sdwa v0, v15, v179 dst_sel:DWORD dst_unused:UNUSED_PAD src0_sel:WORD_1 src1_sel:DWORD
	v_and_b32_sdwa v7, v14, v179 dst_sel:DWORD dst_unused:UNUSED_PAD src0_sel:WORD_1 src1_sel:DWORD
	v_add3_u32 v7, v14, v7, s14
	v_add3_u32 v0, v15, v0, s14
	v_and_b32_sdwa v14, v13, v179 dst_sel:DWORD dst_unused:UNUSED_PAD src0_sel:WORD_1 src1_sel:DWORD
	v_and_b32_sdwa v15, v12, v179 dst_sel:DWORD dst_unused:UNUSED_PAD src0_sel:WORD_1 src1_sel:DWORD
	v_add3_u32 v13, v13, v14, s14
	v_add3_u32 v12, v12, v15, s14
	v_and_b32_e32 v13, 0xffff0000, v13
	v_and_b32_e32 v12, 0xffff0000, v12
	v_or_b32_sdwa v13, v13, v0 dst_sel:DWORD dst_unused:UNUSED_PAD src0_sel:DWORD src1_sel:WORD_1
	v_or_b32_sdwa v12, v12, v7 dst_sel:DWORD dst_unused:UNUSED_PAD src0_sel:DWORD src1_sel:WORD_1
	global_store_dwordx2 v[8:9], v[12:13], off offset:32
	v_mov_b64_e32 v[12:13], v[86:87]
	v_mov_b32_e32 v16, v28
	v_mov_b64_e32 v[10:11], v[88:89]
	v_mov_b32_e32 v17, v26
	v_mov_b32_e32 v26, v29
	s_nop 0
	v_lshlrev_b32_e32 v0, 16, v13
	v_lshlrev_b32_e32 v7, 16, v12
	v_mul_f32_e32 v14, 0xbfb8aa3b, v7
	v_and_b32_e32 v18, 0xffff0000, v13
	v_mul_f32_e32 v13, 0xbfb8aa3b, v0
	v_exp_f32_e32 v14, v14
	v_exp_f32_e32 v15, v13
	v_and_b32_e32 v19, 0xffff0000, v12
	v_mul_f32_e32 v12, 0xbfb8aa3b, v19
	v_exp_f32_e32 v12, v12
	v_pk_add_f32 v[14:15], v[14:15], 1.0 op_sel_hi:[1,0]
	v_pk_mul_f32 v[16:17], v[16:17], v[6:7] op_sel_hi:[1,0]
	v_div_scale_f32 v13, s[12:13], v15, v15, v0
	v_rcp_f32_e32 v20, v13
	s_nop 0
	v_fma_f32 v21, -v13, v20, 1.0
	v_fmac_f32_e32 v20, v21, v20
	v_div_scale_f32 v21, vcc, v0, v15, v0
	v_mul_f32_e32 v22, v21, v20
	v_fma_f32 v23, -v13, v22, v21
	v_fmac_f32_e32 v22, v23, v20
	v_fma_f32 v13, -v13, v22, v21
	v_div_fmas_f32 v13, v13, v20, v22
	v_div_fixup_f32 v15, v13, v15, v0
	v_div_scale_f32 v0, s[12:13], v14, v14, v7
	v_rcp_f32_e32 v13, v0
	s_nop 0
	v_fma_f32 v20, -v0, v13, 1.0
	v_fmac_f32_e32 v13, v20, v13
	v_div_scale_f32 v20, vcc, v7, v14, v7
	v_mul_f32_e32 v21, v20, v13
	v_fma_f32 v22, -v0, v21, v20
	v_fmac_f32_e32 v21, v22, v13
	v_fma_f32 v0, -v0, v21, v20
	v_div_fmas_f32 v0, v0, v13, v21
	v_div_fixup_f32 v14, v0, v14, v7
	v_mul_f32_e32 v0, 0xbfb8aa3b, v18
	v_exp_f32_e32 v13, v0
	v_pk_mul_f32 v[14:15], v[14:15], v[16:17]
	v_pk_mul_f32 v[16:17], v[26:27], v[6:7] op_sel_hi:[1,0]
	v_pk_add_f32 v[12:13], v[12:13], 1.0 op_sel_hi:[1,0]
	s_nop 0
	v_div_scale_f32 v0, s[12:13], v13, v13, v18
	v_rcp_f32_e32 v7, v0
	s_nop 0
	v_fma_f32 v20, -v0, v7, 1.0
	v_fmac_f32_e32 v7, v20, v7
	v_div_scale_f32 v20, vcc, v18, v13, v18
	v_mul_f32_e32 v21, v20, v7
	v_fma_f32 v22, -v0, v21, v20
	v_fmac_f32_e32 v21, v22, v7
	v_fma_f32 v0, -v0, v21, v20
	v_div_fmas_f32 v0, v0, v7, v21
	v_div_fixup_f32 v13, v0, v13, v18
	v_div_scale_f32 v0, s[12:13], v12, v12, v19
	v_rcp_f32_e32 v7, v0
	s_nop 0
	v_fma_f32 v18, -v0, v7, 1.0
	v_fmac_f32_e32 v7, v18, v7
	v_div_scale_f32 v18, vcc, v19, v12, v19
	v_mul_f32_e32 v20, v18, v7
	v_fma_f32 v21, -v0, v20, v18
; __device__ __forceinline__ unsigned pk2(float lo, float hi) { return f2bf(lo) | (f2bf(hi) << 16); }
; __device__ __forceinline__ float bflo(unsigned u) { return __uint_as_float(u << 16); }
; __device__ __forceinline__ float bfhi(unsigned u) { return __uint_as_float(u & 0xffff0000u); }
; __device__ __forceinline__ float silu_f(float v) { return v / (1.f + __expf(-v)); }
; __device__ __forceinline__ void ret2_task(const Params& p_, int l, int task, unsigned char* lds) {
;     ...
;     for (int et = 0; et < 4; ++et) { const u32x2 gz = *(const u32x2*)(Z + tok * DIN + 9 * DG + h * 64 + 16 * et + 4 * fq); u32x2 o;
;         o.x = pk2(tot[et][0] * rs * silu_f(bflo(gz.x)), tot[et][1] * rs * silu_f(bfhi(gz.x))); o.y = pk2(tot[et][2] * rs * silu_f(bflo(gz.y)), tot[et][3] * rs * silu_f(bfhi(gz.y)));
;         *(u32x2*)(CAT + tok * DM + 1024 + h * 64 + 16 * et + 4 * fq) = o; }
;     __syncthreads();
	v_fmac_f32_e32 v20, v21, v7
	v_fma_f32 v0, -v0, v20, v18
	v_div_fmas_f32 v0, v0, v7, v20
	v_div_fixup_f32 v12, v0, v12, v19
	v_pk_mul_f32 v[12:13], v[12:13], v[16:17]
	v_and_b32_sdwa v0, v15, v179 dst_sel:DWORD dst_unused:UNUSED_PAD src0_sel:WORD_1 src1_sel:DWORD
	v_and_b32_sdwa v7, v14, v179 dst_sel:DWORD dst_unused:UNUSED_PAD src0_sel:WORD_1 src1_sel:DWORD
	v_add3_u32 v7, v14, v7, s14
	v_add3_u32 v0, v15, v0, s14
	v_and_b32_sdwa v14, v13, v179 dst_sel:DWORD dst_unused:UNUSED_PAD src0_sel:WORD_1 src1_sel:DWORD
	v_and_b32_sdwa v15, v12, v179 dst_sel:DWORD dst_unused:UNUSED_PAD src0_sel:WORD_1 src1_sel:DWORD
	v_add3_u32 v13, v13, v14, s14
	v_add3_u32 v12, v12, v15, s14
	v_and_b32_e32 v13, 0xffff0000, v13
	v_and_b32_e32 v12, 0xffff0000, v12
	v_or_b32_sdwa v13, v13, v0 dst_sel:DWORD dst_unused:UNUSED_PAD src0_sel:DWORD src1_sel:WORD_1
	v_or_b32_sdwa v12, v12, v7 dst_sel:DWORD dst_unused:UNUSED_PAD src0_sel:DWORD src1_sel:WORD_1
	s_nop 0
	v_lshlrev_b32_e32 v0, 16, v11
	v_lshlrev_b32_e32 v7, 16, v10
	global_store_dwordx2 v[8:9], v[12:13], off offset:64
	v_mul_f32_e32 v12, 0xbfb8aa3b, v7
	v_mov_b32_e32 v15, v2
	v_mul_f32_e32 v2, 0xbfb8aa3b, v0
	v_exp_f32_e32 v12, v12
	v_exp_f32_e32 v13, v2
	v_mov_b32_e32 v14, v4
	v_and_b32_e32 v16, 0xffff0000, v11
	v_and_b32_e32 v17, 0xffff0000, v10
	v_pk_add_f32 v[12:13], v[12:13], 1.0 op_sel_hi:[1,0]
	v_mul_f32_e32 v10, 0xbfb8aa3b, v17
	v_div_scale_f32 v2, s[12:13], v13, v13, v0
	v_rcp_f32_e32 v4, v2
	v_exp_f32_e32 v10, v10
	v_pk_mul_f32 v[14:15], v[14:15], v[6:7] op_sel_hi:[1,0]
	v_fma_f32 v11, -v2, v4, 1.0
	v_fmac_f32_e32 v4, v11, v4
	v_div_scale_f32 v11, vcc, v0, v13, v0
	v_mul_f32_e32 v18, v11, v4
	v_fma_f32 v19, -v2, v18, v11
	v_fmac_f32_e32 v18, v19, v4
	v_fma_f32 v2, -v2, v18, v11
	v_div_fmas_f32 v2, v2, v4, v18
	v_div_fixup_f32 v13, v2, v13, v0
	v_div_scale_f32 v0, s[12:13], v12, v12, v7
	v_rcp_f32_e32 v2, v0
	s_nop 0
	v_fma_f32 v4, -v0, v2, 1.0
	v_fmac_f32_e32 v2, v4, v2
	v_div_scale_f32 v4, vcc, v7, v12, v7
	v_mul_f32_e32 v11, v4, v2
	v_fma_f32 v18, -v0, v11, v4
	v_fmac_f32_e32 v11, v18, v2
	v_fma_f32 v0, -v0, v11, v4
	v_div_fmas_f32 v0, v0, v2, v11
	v_div_fixup_f32 v12, v0, v12, v7
	v_mul_f32_e32 v0, 0xbfb8aa3b, v16
	v_exp_f32_e32 v11, v0
	v_mov_b32_e32 v2, v5
	v_pk_mul_f32 v[2:3], v[2:3], v[6:7] op_sel_hi:[1,0]
	v_pk_mul_f32 v[12:13], v[14:15], v[12:13]
	v_pk_add_f32 v[4:5], v[10:11], 1.0 op_sel_hi:[1,0]
	s_nop 0
	v_div_scale_f32 v0, s[12:13], v5, v5, v16
	v_rcp_f32_e32 v6, v0
	s_nop 0
	v_fma_f32 v7, -v0, v6, 1.0
	v_fmac_f32_e32 v6, v7, v6
	v_div_scale_f32 v7, vcc, v16, v5, v16
	v_mul_f32_e32 v10, v7, v6
	v_fma_f32 v11, -v0, v10, v7
	v_fmac_f32_e32 v10, v11, v6
	v_fma_f32 v0, -v0, v10, v7
	v_div_fmas_f32 v0, v0, v6, v10
	v_div_fixup_f32 v5, v0, v5, v16
	v_div_scale_f32 v0, s[12:13], v4, v4, v17
	v_rcp_f32_e32 v6, v0
	s_nop 0
	v_fma_f32 v7, -v0, v6, 1.0
	v_fmac_f32_e32 v6, v7, v6
	v_div_scale_f32 v7, vcc, v17, v4, v17
	v_mul_f32_e32 v10, v7, v6
	v_fma_f32 v11, -v0, v10, v7
	v_fmac_f32_e32 v10, v11, v6
	v_fma_f32 v0, -v0, v10, v7
	v_div_fmas_f32 v0, v0, v6, v10
	v_div_fixup_f32 v4, v0, v4, v17
	v_pk_mul_f32 v[2:3], v[2:3], v[4:5]
	v_and_b32_sdwa v0, v13, v179 dst_sel:DWORD dst_unused:UNUSED_PAD src0_sel:WORD_1 src1_sel:DWORD
	v_and_b32_sdwa v5, v3, v179 dst_sel:DWORD dst_unused:UNUSED_PAD src0_sel:WORD_1 src1_sel:DWORD
	v_and_b32_sdwa v6, v2, v179 dst_sel:DWORD dst_unused:UNUSED_PAD src0_sel:WORD_1 src1_sel:DWORD
	v_and_b32_sdwa v4, v12, v179 dst_sel:DWORD dst_unused:UNUSED_PAD src0_sel:WORD_1 src1_sel:DWORD
	v_add3_u32 v3, v3, v5, s14
	v_add3_u32 v2, v2, v6, s14
	v_add3_u32 v4, v12, v4, s14
	v_add3_u32 v0, v13, v0, s14
	v_and_b32_e32 v3, 0xffff0000, v3
	v_and_b32_e32 v2, 0xffff0000, v2
	v_or_b32_sdwa v3, v3, v0 dst_sel:DWORD dst_unused:UNUSED_PAD src0_sel:DWORD src1_sel:WORD_1
	v_or_b32_sdwa v2, v2, v4 dst_sel:DWORD dst_unused:UNUSED_PAD src0_sel:DWORD src1_sel:WORD_1
	global_store_dwordx2 v[8:9], v[2:3], off offset:96
	s_barrier
	s_cbranch_scc0 .LBB0_577
